# w_out_ab conversion moved to the idle workgroups of phase 3; phase 0 falls back to the baseline distribution on a grid other than 256
# speedup vs baseline: 1.0640x; 1.0056x over previous
; #define LAS __attribute__((address_space(3)))
; DI int lane_id() { int l = __builtin_amdgcn_mbcnt_hi(-1, __builtin_amdgcn_mbcnt_lo(-1, 0)); asm volatile("" : "+v"(l)); return l; }
; DI void phase0(CP& p, LAS unsigned char* lds, int wid) {
;     const int lane = lane_id(), tid = wid * 64 + lane;
;     constexpr int NCONV = 5520, NXROW = 8192;
;     const int gw = blockIdx.x * 8 + wid, nw = gridDim.x * 8;
;     for (int it0 = gw; it0 < NCONV + NXROW; it0 += nw) {
;         const int it = it0 < NCONV ? NCONV - 1 - it0 : it0;
;         if (it < NCONV) {
;             const float* src; const float* src2 = nullptr; const float* gain = nullptr; bf16_t* dst; int ld, K, mode = CM_ID, coff = 0, t0;
.Lconv_entry:
	s_lshl_b32 s2, s6, 3
	v_mbcnt_hi_u32_b32 v5, -1, v254
	s_add_i32 s89, s33, s2
	s_cmp_lg_u32 s98, 0
	s_cbranch_scc1 .Lconv_ext
	s_movk_i32 s101, 0x358f
	s_cmpk_lg_i32 s7, 0x100
	s_cbranch_scc1 .Lconv_go
	s_mul_i32 s89, s33, s7
	s_add_i32 s89, s89, s6
	s_addk_i32 s89, 5136
	s_branch .Lconv_go

; DI void phase0(CP& p, LAS unsigned char* lds, int wid) {
;     ...
;     const int gt = blockIdx.x * NTHR + tid, gs = gridDim.x * NTHR;
;     for (int i = gt; i < 7 * 8192; i += gs) SSQ(1)[i] = 0.f;
.LBB0_225:
	s_cmp_eq_u32 s98, 1
	s_cbranch_scc1 .Lconv_ret_1
	s_cmp_eq_u32 s98, 2
	s_cbranch_scc1 .Lconv_ret_2
	s_cmp_eq_u32 s98, 3
	s_cbranch_scc1 .Lconv_ret_3
	s_cmp_eq_u32 s98, 4
	s_cbranch_scc1 .Lconv_ret_4
	s_cmp_eq_u32 s98, 5
	s_cbranch_scc1 .Lconv_tout_5
	s_cmp_eq_u32 s98, 6
	s_cbranch_scc1 .Lconv_tout_6
	s_cmp_eq_u32 s98, 7
	s_cbranch_scc1 .Lconv_tout_7
	s_load_dwordx2 s[4:5], s[38:39], 0xa8
	s_and_b32 s2, s88, 0xffffffc0
	s_lshl_b32 s3, s6, 9
	s_add_i32 s2, s2, s3
	v_add_u32_e32 v2, s2, v0
	s_mov_b32 s2, 0xe000
	s_waitcnt lgkmcnt(0)
	s_lshl_b32 s10, s7, 9
	v_cmp_gt_i32_e32 vcc, s2, v2
	s_and_saveexec_b64 s[8:9], vcc
	s_cbranch_execz .LBB0_233
	v_cvt_f32_u32_e32 v1, s10
	v_add_u32_e32 v3, s10, v2
	v_mov_b32_e32 v4, s10
	v_cmp_gt_i32_e32 vcc, s2, v3
	v_rcp_iflag_f32_e32 v1, v1
	s_sub_i32 s11, 0, s10
	v_max_i32_e32 v5, 0xe000, v3
	v_addc_co_u32_e64 v4, s[2:3], v2, v4, vcc
	v_mul_f32_e32 v1, 0x4f7ffffe, v1
	v_cvt_u32_f32_e32 v1, v1
	v_sub_u32_e32 v4, v5, v4
	s_mov_b64 s[12:13], -1
	v_mul_lo_u32 v5, s11, v1
	v_mul_hi_u32 v5, v1, v5
	v_add_u32_e32 v1, v1, v5
	v_mul_hi_u32 v1, v4, v1
	v_mul_lo_u32 v5, v1, s10
	v_sub_u32_e32 v4, v4, v5
	v_add_u32_e32 v6, 1, v1
	v_cmp_le_u32_e64 s[2:3], s10, v4
	v_subrev_u32_e32 v5, s10, v4
	s_nop 0
	v_cndmask_b32_e64 v1, v1, v6, s[2:3]
	v_cndmask_b32_e64 v4, v4, v5, s[2:3]
	v_add_u32_e32 v5, 1, v1
	v_cmp_le_u32_e64 s[2:3], s10, v4
	v_mov_b32_e32 v4, v2
	s_nop 0
	v_cndmask_b32_e64 v1, v1, v5, s[2:3]
	v_addc_co_u32_e32 v1, vcc, 1, v1, vcc
	v_cmp_lt_u32_e32 vcc, 1, v1
	s_and_saveexec_b64 s[2:3], vcc
	s_cbranch_execz .LBB0_230
	s_add_u32 s12, s4, 0xcd08000
	s_addc_u32 s13, s5, 0
	v_and_b32_e32 v6, -2, v1
	s_lshl_b32 s11, s7, 10
	s_mov_b32 s16, s11
	s_mov_b64 s[14:15], 0
	v_mov_b32_e32 v7, 0
	v_mov_b32_e32 v8, v6
	v_mov_b64_e32 v[4:5], v[2:3]

; DI void phase0(CP& p, LAS unsigned char* lds, int wid) {
;     ...
;     for (int it0 = gw; it0 < NCONV + NXROW; it0 += nw) {
;         const int it = it0 < NCONV ? NCONV - 1 - it0 : it0;
;         if (it < NCONV) {
;             const float* src; const float* src2 = nullptr; const float* gain = nullptr; bf16_t* dst; int ld, K, mode = CM_ID, coff = 0, t0;
;             if (it < 256) { src = p.w_in_ab; gain = p.g_mix; dst = WSB(OFF_W1UZ); ld = 3072; K = 2048; mode = CM_UZ; t0 = 0; }
;             else if (it < 384) { src = p.w_in_ab; gain = p.g_mix; dst = WSB(OFF_W1V); ld = 3072; K = 2048; coff = 1024; t0 = 256; }
;             else if (it < 640) { src = p.w_out_ab; dst = WSB(OFF_WOAB); ld = 2048; K = 2048; mode = CM_P32; t0 = 384; }
;             else if (it < 2048) { src = p.w_gate; src2 = p.w_up; gain = p.g_ffn; dst = WSB(OFF_WGU0); ld = DFF; K = 2048; mode = CM_GU; t0 = 640; }
;             else if (it < 2752) { src = p.w_down; dst = WSB(OFF_WD0); ld = 2048; K = DFF; mode = CM_P32; t0 = 2048; }
;             else if (it < 2768) { src = p.w_pool; dst = WSB(OFF_WPOOL); ld = 256; K = 256; mode = CM_POOL; t0 = 2752; }
;             else if (it < 2928) { src = p.w_in_c; gain = p.g_mix + 2048; dst = WSB(OFF_WINC); ld = 1088; K = 2048; mode = CM_INC; t0 = 2768; }
;             else if (it < 3024) { src = p.w_uq; gain = p.g_cq; dst = WSB(OFF_WUQ); ld = 3072; K = 512; mode = CM_UQ; t0 = 2928; }
;             else if (it < 3088) { src = p.w_ukv; gain = p.g_ckv; dst = WSB(OFF_WUKK); ld = 4096; K = 512; mode = CM_UKVK; t0 = 3024; }
;             else if (it < 3152) { src = p.w_ukv; gain = p.g_ckv; dst = WSB(OFF_WUKV); ld = 4096; K = 512; mode = CM_UKVV; t0 = 3088; }
;             else if (it < 3408) { src = p.w_out_c; dst = WSB(OFF_WOC); ld = 2048; K = 2048; mode = CM_P32; t0 = 3152; }
;             else if (it < 4816) { src = p.w_gate + (size_t)2048 * DFF; src2 = p.w_up + (size_t)2048 * DFF; gain = p.g_ffn + 2048; dst = WSB(OFF_WGU1); ld = DFF; K = 2048; mode = CM_GU; t0 = 3408; }
;             else { src = p.w_down + (size_t)DFF * 2048; dst = WSB(OFF_WD1); ld = 2048; K = DFF; mode = CM_P32; t0 = 4816; }
;             conv_item(lane, lds + wid * 9216, src, src2, gain, dst, ld, K, mode, coff, it - t0);
.LBB0_398:
	s_and_b64 vcc, exec, s[8:9]
	s_cbranch_vccz .Lconv_skip_0
	s_cmpk_eq_i32 s7, 0x100
	s_cbranch_scc0 .Lconv_skip_0
	s_and_b32 s12, s6, 31
	s_lshl_b32 s12, s12, 3
	s_lshr_b32 s13, s6, 5
	s_or_b32 s12, s12, s13
	s_cmpk_lt_u32 s12, 128
	s_cbranch_scc1 .Lconv_skip_0
	s_and_b32 s12, s6, 31
	s_lshl_b32 s12, s12, 3
	s_lshr_b32 s13, s6, 5
	s_or_b32 s12, s12, s13
	s_addk_i32 s12, -128
	s_mul_i32 s13, s33, 128
	s_add_i32 s12, s12, s13
	s_add_i32 s99, s12, 3472
	s_movk_i32 s101, 4879
	s_movk_i32 s100, 1024
	s_mov_b32 s98, 1
	s_branch .Lconv_entry

; DI void phase0(CP& p, LAS unsigned char* lds, int wid) {
;     ...
;     for (int it0 = gw; it0 < NCONV + NXROW; it0 += nw) {
;         const int it = it0 < NCONV ? NCONV - 1 - it0 : it0;
;         if (it < NCONV) {
;             const float* src; const float* src2 = nullptr; const float* gain = nullptr; bf16_t* dst; int ld, K, mode = CM_ID, coff = 0, t0;
;             if (it < 256) { src = p.w_in_ab; gain = p.g_mix; dst = WSB(OFF_W1UZ); ld = 3072; K = 2048; mode = CM_UZ; t0 = 0; }
;             else if (it < 384) { src = p.w_in_ab; gain = p.g_mix; dst = WSB(OFF_W1V); ld = 3072; K = 2048; coff = 1024; t0 = 256; }
;             else if (it < 640) { src = p.w_out_ab; dst = WSB(OFF_WOAB); ld = 2048; K = 2048; mode = CM_P32; t0 = 384; }
;             else if (it < 2048) { src = p.w_gate; src2 = p.w_up; gain = p.g_ffn; dst = WSB(OFF_WGU0); ld = DFF; K = 2048; mode = CM_GU; t0 = 640; }
;             else if (it < 2752) { src = p.w_down; dst = WSB(OFF_WD0); ld = 2048; K = DFF; mode = CM_P32; t0 = 2048; }
;             else if (it < 2768) { src = p.w_pool; dst = WSB(OFF_WPOOL); ld = 256; K = 256; mode = CM_POOL; t0 = 2752; }
;             else if (it < 2928) { src = p.w_in_c; gain = p.g_mix + 2048; dst = WSB(OFF_WINC); ld = 1088; K = 2048; mode = CM_INC; t0 = 2768; }
;             else if (it < 3024) { src = p.w_uq; gain = p.g_cq; dst = WSB(OFF_WUQ); ld = 3072; K = 512; mode = CM_UQ; t0 = 2928; }
;             else if (it < 3088) { src = p.w_ukv; gain = p.g_ckv; dst = WSB(OFF_WUKK); ld = 4096; K = 512; mode = CM_UKVK; t0 = 3024; }
;             else if (it < 3152) { src = p.w_ukv; gain = p.g_ckv; dst = WSB(OFF_WUKV); ld = 4096; K = 512; mode = CM_UKVV; t0 = 3088; }
;             else if (it < 3408) { src = p.w_out_c; dst = WSB(OFF_WOC); ld = 2048; K = 2048; mode = CM_P32; t0 = 3152; }
;             else if (it < 4816) { src = p.w_gate + (size_t)2048 * DFF; src2 = p.w_up + (size_t)2048 * DFF; gain = p.g_ffn + 2048; dst = WSB(OFF_WGU1); ld = DFF; K = 2048; mode = CM_GU; t0 = 3408; }
;             else { src = p.w_down + (size_t)DFF * 2048; dst = WSB(OFF_WD1); ld = 2048; K = DFF; mode = CM_P32; t0 = 4816; }
;             conv_item(lane, lds + wid * 9216, src, src2, gain, dst, ld, K, mode, coff, it - t0);
.LBB0_546:
	s_and_b64 vcc, exec, s[4:5]
	s_cbranch_vccz .Lconv_skip_1
	s_cmpk_eq_i32 s7, 0x100
	s_cbranch_scc0 .Lconv_skip_1
	s_and_b32 s12, s6, 31
	s_lshl_b32 s12, s12, 3
	s_lshr_b32 s13, s6, 5
	s_or_b32 s12, s12, s13
	s_cmpk_lt_u32 s12, 128
	s_cbranch_scc1 .Lconv_skip_1
	s_and_b32 s12, s6, 31
	s_lshl_b32 s12, s12, 3
	s_lshr_b32 s13, s6, 5
	s_or_b32 s12, s12, s13
	s_addk_i32 s12, -128
	s_mul_i32 s13, s33, 128
	s_add_i32 s12, s12, s13
	s_add_i32 s99, s12, 4880
	s_movk_i32 s101, 5135
	s_movk_i32 s100, 16384
	s_mov_b32 s98, 3
	s_branch .Lconv_entry
.Lconv_ret_3:
	s_mov_b32 s98, 0
	s_cmp_lt_i32 s34, 4
	s_cselect_b64 s[4:5], -1, 0
	s_cmp_gt_i32 s35, 3
	s_cselect_b64 s[10:11], -1, 0
	s_and_b64 s[4:5], s[4:5], s[10:11]

; DI void phase0(CP& p, LAS unsigned char* lds, int wid) {
;     ...
;     for (int it0 = gw; it0 < NCONV + NXROW; it0 += nw) {
;         const int it = it0 < NCONV ? NCONV - 1 - it0 : it0;
;         if (it < NCONV) {
;             const float* src; const float* src2 = nullptr; const float* gain = nullptr; bf16_t* dst; int ld, K, mode = CM_ID, coff = 0, t0;
;             if (it < 256) { src = p.w_in_ab; gain = p.g_mix; dst = WSB(OFF_W1UZ); ld = 3072; K = 2048; mode = CM_UZ; t0 = 0; }
;             else if (it < 384) { src = p.w_in_ab; gain = p.g_mix; dst = WSB(OFF_W1V); ld = 3072; K = 2048; coff = 1024; t0 = 256; }
;             else if (it < 640) { src = p.w_out_ab; dst = WSB(OFF_WOAB); ld = 2048; K = 2048; mode = CM_P32; t0 = 384; }
;             else if (it < 2048) { src = p.w_gate; src2 = p.w_up; gain = p.g_ffn; dst = WSB(OFF_WGU0); ld = DFF; K = 2048; mode = CM_GU; t0 = 640; }
;             else if (it < 2752) { src = p.w_down; dst = WSB(OFF_WD0); ld = 2048; K = DFF; mode = CM_P32; t0 = 2048; }
;             else if (it < 2768) { src = p.w_pool; dst = WSB(OFF_WPOOL); ld = 256; K = 256; mode = CM_POOL; t0 = 2752; }
;             else if (it < 2928) { src = p.w_in_c; gain = p.g_mix + 2048; dst = WSB(OFF_WINC); ld = 1088; K = 2048; mode = CM_INC; t0 = 2768; }
;             else if (it < 3024) { src = p.w_uq; gain = p.g_cq; dst = WSB(OFF_WUQ); ld = 3072; K = 512; mode = CM_UQ; t0 = 2928; }
;             else if (it < 3088) { src = p.w_ukv; gain = p.g_ckv; dst = WSB(OFF_WUKK); ld = 4096; K = 512; mode = CM_UKVK; t0 = 3024; }
;             else if (it < 3152) { src = p.w_ukv; gain = p.g_ckv; dst = WSB(OFF_WUKV); ld = 4096; K = 512; mode = CM_UKVV; t0 = 3088; }
;             else if (it < 3408) { src = p.w_out_c; dst = WSB(OFF_WOC); ld = 2048; K = 2048; mode = CM_P32; t0 = 3152; }
;             else if (it < 4816) { src = p.w_gate + (size_t)2048 * DFF; src2 = p.w_up + (size_t)2048 * DFF; gain = p.g_ffn + 2048; dst = WSB(OFF_WGU1); ld = DFF; K = 2048; mode = CM_GU; t0 = 3408; }
;             else { src = p.w_down + (size_t)DFF * 2048; dst = WSB(OFF_WD1); ld = 2048; K = DFF; mode = CM_P32; t0 = 4816; }
;             conv_item(lane, lds + wid * 9216, src, src2, gain, dst, ld, K, mode, coff, it - t0);
.LBB0_710:
	s_and_b64 vcc, exec, s[4:5]
	s_cbranch_vccz .Lconv_skip_2
	s_cmpk_eq_i32 s7, 0x100
	s_cbranch_scc0 .Lconv_skip_2
	s_and_b32 s12, s6, 31
	s_lshl_b32 s12, s12, 3
	s_lshr_b32 s13, s6, 5
	s_or_b32 s12, s12, s13
	s_cmpk_lt_u32 s12, 128
	s_cbranch_scc1 .Lconv_skip_2
	s_and_b32 s12, s6, 31
	s_lshl_b32 s12, s12, 3
	s_lshr_b32 s13, s6, 5
	s_or_b32 s12, s12, s13
	s_addk_i32 s12, -128
	s_mul_i32 s13, s33, 128
	s_add_i32 s12, s12, s13
	s_add_i32 s99, s12, 2368
	s_movk_i32 s101, 3471
	s_movk_i32 s100, 1024
	s_mov_b32 s98, 4
	s_branch .Lconv_entry

; DI void phase0(CP& p, LAS unsigned char* lds, int wid) {
;     ...
;     for (int it0 = gw; it0 < NCONV + NXROW; it0 += nw) {
;         const int it = it0 < NCONV ? NCONV - 1 - it0 : it0;
;         if (it < NCONV) {
;             const float* src; const float* src2 = nullptr; const float* gain = nullptr; bf16_t* dst; int ld, K, mode = CM_ID, coff = 0, t0;
;             if (it < 256) { src = p.w_in_ab; gain = p.g_mix; dst = WSB(OFF_W1UZ); ld = 3072; K = 2048; mode = CM_UZ; t0 = 0; }
;             else if (it < 384) { src = p.w_in_ab; gain = p.g_mix; dst = WSB(OFF_W1V); ld = 3072; K = 2048; coff = 1024; t0 = 256; }
;             else if (it < 640) { src = p.w_out_ab; dst = WSB(OFF_WOAB); ld = 2048; K = 2048; mode = CM_P32; t0 = 384; }
;             else if (it < 2048) { src = p.w_gate; src2 = p.w_up; gain = p.g_ffn; dst = WSB(OFF_WGU0); ld = DFF; K = 2048; mode = CM_GU; t0 = 640; }
;             else if (it < 2752) { src = p.w_down; dst = WSB(OFF_WD0); ld = 2048; K = DFF; mode = CM_P32; t0 = 2048; }
;             else if (it < 2768) { src = p.w_pool; dst = WSB(OFF_WPOOL); ld = 256; K = 256; mode = CM_POOL; t0 = 2752; }
;             else if (it < 2928) { src = p.w_in_c; gain = p.g_mix + 2048; dst = WSB(OFF_WINC); ld = 1088; K = 2048; mode = CM_INC; t0 = 2768; }
;             else if (it < 3024) { src = p.w_uq; gain = p.g_cq; dst = WSB(OFF_WUQ); ld = 3072; K = 512; mode = CM_UQ; t0 = 2928; }
;             else if (it < 3088) { src = p.w_ukv; gain = p.g_ckv; dst = WSB(OFF_WUKK); ld = 4096; K = 512; mode = CM_UKVK; t0 = 3024; }
;             else if (it < 3152) { src = p.w_ukv; gain = p.g_ckv; dst = WSB(OFF_WUKV); ld = 4096; K = 512; mode = CM_UKVV; t0 = 3088; }
;             else if (it < 3408) { src = p.w_out_c; dst = WSB(OFF_WOC); ld = 2048; K = 2048; mode = CM_P32; t0 = 3152; }
;             else if (it < 4816) { src = p.w_gate + (size_t)2048 * DFF; src2 = p.w_up + (size_t)2048 * DFF; gain = p.g_ffn + 2048; dst = WSB(OFF_WGU1); ld = DFF; K = 2048; mode = CM_GU; t0 = 3408; }
;             else { src = p.w_down + (size_t)DFF * 2048; dst = WSB(OFF_WD1); ld = 2048; K = DFF; mode = CM_P32; t0 = 4816; }
;             conv_item(lane, lds + wid * 9216, src, src2, gain, dst, ld, K, mode, coff, it - t0);
.LBB0_898:
	s_and_b64 vcc, exec, s[8:9]
	s_cbranch_vccz .Lconv_skip_3
	s_cmpk_eq_i32 s7, 0x100
	s_cbranch_scc0 .Lconv_skip_3
	s_and_b32 s12, s6, 31
	s_lshl_b32 s12, s12, 3
	s_lshr_b32 s13, s6, 5
	s_or_b32 s12, s12, s13
	s_cmpk_lt_u32 s12, 160
	s_cbranch_scc1 .Lconv_skip_3
	s_and_b32 s12, s6, 31
	s_lshl_b32 s12, s12, 3
	s_lshr_b32 s13, s6, 5
	s_or_b32 s12, s12, s13
	s_addk_i32 s12, -160
	s_mul_i32 s13, s33, 96
	s_add_i32 s12, s12, s13
	s_add_i32 s99, s12, 832
	s_movk_i32 s101, 2367
	s_movk_i32 s100, 768
	s_mov_b32 s98, 5
	s_branch .Lconv_tin

; DI void phase0(CP& p, LAS unsigned char* lds, int wid) {
;     ...
;     for (int it0 = gw; it0 < NCONV + NXROW; it0 += nw) {
;         const int it = it0 < NCONV ? NCONV - 1 - it0 : it0;
;         if (it < NCONV) {
;             const float* src; const float* src2 = nullptr; const float* gain = nullptr; bf16_t* dst; int ld, K, mode = CM_ID, coff = 0, t0;
;             if (it < 256) { src = p.w_in_ab; gain = p.g_mix; dst = WSB(OFF_W1UZ); ld = 3072; K = 2048; mode = CM_UZ; t0 = 0; }
;             else if (it < 384) { src = p.w_in_ab; gain = p.g_mix; dst = WSB(OFF_W1V); ld = 3072; K = 2048; coff = 1024; t0 = 256; }
;             else if (it < 640) { src = p.w_out_ab; dst = WSB(OFF_WOAB); ld = 2048; K = 2048; mode = CM_P32; t0 = 384; }
;             else if (it < 2048) { src = p.w_gate; src2 = p.w_up; gain = p.g_ffn; dst = WSB(OFF_WGU0); ld = DFF; K = 2048; mode = CM_GU; t0 = 640; }
;             else if (it < 2752) { src = p.w_down; dst = WSB(OFF_WD0); ld = 2048; K = DFF; mode = CM_P32; t0 = 2048; }
;             else if (it < 2768) { src = p.w_pool; dst = WSB(OFF_WPOOL); ld = 256; K = 256; mode = CM_POOL; t0 = 2752; }
;             else if (it < 2928) { src = p.w_in_c; gain = p.g_mix + 2048; dst = WSB(OFF_WINC); ld = 1088; K = 2048; mode = CM_INC; t0 = 2768; }
;             else if (it < 3024) { src = p.w_uq; gain = p.g_cq; dst = WSB(OFF_WUQ); ld = 3072; K = 512; mode = CM_UQ; t0 = 2928; }
;             else if (it < 3088) { src = p.w_ukv; gain = p.g_ckv; dst = WSB(OFF_WUKK); ld = 4096; K = 512; mode = CM_UKVK; t0 = 3024; }
;             else if (it < 3152) { src = p.w_ukv; gain = p.g_ckv; dst = WSB(OFF_WUKV); ld = 4096; K = 512; mode = CM_UKVV; t0 = 3088; }
;             else if (it < 3408) { src = p.w_out_c; dst = WSB(OFF_WOC); ld = 2048; K = 2048; mode = CM_P32; t0 = 3152; }
;             else if (it < 4816) { src = p.w_gate + (size_t)2048 * DFF; src2 = p.w_up + (size_t)2048 * DFF; gain = p.g_ffn + 2048; dst = WSB(OFF_WGU1); ld = DFF; K = 2048; mode = CM_GU; t0 = 3408; }
;             else { src = p.w_down + (size_t)DFF * 2048; dst = WSB(OFF_WD1); ld = 2048; K = DFF; mode = CM_P32; t0 = 4816; }
;             conv_item(lane, lds + wid * 9216, src, src2, gain, dst, ld, K, mode, coff, it - t0);
.LBB0_1017:
	s_and_b64 vcc, exec, s[2:3]
	s_cbranch_vccz .Lconv_skip_4
	s_cmpk_eq_i32 s7, 0x100
	s_cbranch_scc0 .Lconv_skip_4
	s_and_b32 s12, s6, 31
	s_lshl_b32 s12, s12, 3
	s_lshr_b32 s13, s6, 5
	s_or_b32 s12, s12, s13
	s_cmpk_lt_u32 s12, 128
	s_cbranch_scc1 .Lconv_skip_4
	s_and_b32 s12, s6, 31
	s_lshl_b32 s12, s12, 3
	s_lshr_b32 s13, s6, 5
	s_or_b32 s12, s12, s13
	s_addk_i32 s12, -128
	s_mul_i32 s13, s33, 128
	s_add_i32 s12, s12, s13
	s_add_i32 s99, s12, 704
	s_movk_i32 s101, 831
	s_movk_i32 s100, 16384
	s_mov_b32 s98, 6
	s_branch .Lconv_tin

; DI void phase0(CP& p, LAS unsigned char* lds, int wid) {
;     ...
;     for (int it0 = gw; it0 < NCONV + NXROW; it0 += nw) {
;         const int it = it0 < NCONV ? NCONV - 1 - it0 : it0;
;         if (it < NCONV) {
;             const float* src; const float* src2 = nullptr; const float* gain = nullptr; bf16_t* dst; int ld, K, mode = CM_ID, coff = 0, t0;
;             if (it < 256) { src = p.w_in_ab; gain = p.g_mix; dst = WSB(OFF_W1UZ); ld = 3072; K = 2048; mode = CM_UZ; t0 = 0; }
;             else if (it < 384) { src = p.w_in_ab; gain = p.g_mix; dst = WSB(OFF_W1V); ld = 3072; K = 2048; coff = 1024; t0 = 256; }
;             else if (it < 640) { src = p.w_out_ab; dst = WSB(OFF_WOAB); ld = 2048; K = 2048; mode = CM_P32; t0 = 384; }
;             else if (it < 2048) { src = p.w_gate; src2 = p.w_up; gain = p.g_ffn; dst = WSB(OFF_WGU0); ld = DFF; K = 2048; mode = CM_GU; t0 = 640; }
;             else if (it < 2752) { src = p.w_down; dst = WSB(OFF_WD0); ld = 2048; K = DFF; mode = CM_P32; t0 = 2048; }
;             else if (it < 2768) { src = p.w_pool; dst = WSB(OFF_WPOOL); ld = 256; K = 256; mode = CM_POOL; t0 = 2752; }
;             else if (it < 2928) { src = p.w_in_c; gain = p.g_mix + 2048; dst = WSB(OFF_WINC); ld = 1088; K = 2048; mode = CM_INC; t0 = 2768; }
;             else if (it < 3024) { src = p.w_uq; gain = p.g_cq; dst = WSB(OFF_WUQ); ld = 3072; K = 512; mode = CM_UQ; t0 = 2928; }
;             else if (it < 3088) { src = p.w_ukv; gain = p.g_ckv; dst = WSB(OFF_WUKK); ld = 4096; K = 512; mode = CM_UKVK; t0 = 3024; }
;             else if (it < 3152) { src = p.w_ukv; gain = p.g_ckv; dst = WSB(OFF_WUKV); ld = 4096; K = 512; mode = CM_UKVV; t0 = 3088; }
;             else if (it < 3408) { src = p.w_out_c; dst = WSB(OFF_WOC); ld = 2048; K = 2048; mode = CM_P32; t0 = 3152; }
;             else if (it < 4816) { src = p.w_gate + (size_t)2048 * DFF; src2 = p.w_up + (size_t)2048 * DFF; gain = p.g_ffn + 2048; dst = WSB(OFF_WGU1); ld = DFF; K = 2048; mode = CM_GU; t0 = 3408; }
;             else { src = p.w_down + (size_t)DFF * 2048; dst = WSB(OFF_WD1); ld = 2048; K = DFF; mode = CM_P32; t0 = 4816; }
;             conv_item(lane, lds + wid * 9216, src, src2, gain, dst, ld, K, mode, coff, it - t0);
.LBB0_1265:
	s_and_b64 vcc, exec, s[4:5]
	s_cbranch_vccz .Lconv_skip_5
	s_cmpk_eq_i32 s7, 0x100
	s_cbranch_scc0 .Lconv_skip_5
	s_and_b32 s12, s6, 31
	s_lshl_b32 s12, s12, 3
	s_lshr_b32 s13, s6, 5
	s_or_b32 s12, s12, s13
	s_cmpk_lt_u32 s12, 128
	s_cbranch_scc1 .Lconv_skip_5
	s_and_b32 s12, s6, 31
	s_lshl_b32 s12, s12, 3
	s_lshr_b32 s13, s6, 5
	s_or_b32 s12, s12, s13
	s_addk_i32 s12, -128
	s_mul_i32 s13, s33, 128
	s_add_i32 s12, s12, s13
	s_add_i32 s99, s12, 0
	s_movk_i32 s101, 703
	s_movk_i32 s100, 16384
	s_mov_b32 s98, 7
	s_branch .Lconv_tin
